# select classify: count pass builds per-lane 64-bit masks of keys at/above the threshold bin (compare on raw keys, popcount), write pass walks only set bits (sparse) instead of branchy per-key code
# speedup vs baseline: 1.0368x; 1.0356x over previous
.Lidx_loop:
	s_mov_b32 s14, s17
	s_mov_b32 s17, s15
	s_mov_b64 exec, 1
	ds_add_rtn_u32 v171, v172, v149
	s_mov_b64 exec, -1
	s_cmp_gt_i32 s17, s13
	s_cbranch_scc1 .Lidx_dummy0
	s_mov_b32 s6, s17
	s_ashr_i32 s7, s6, 31
	s_lshl_b64 s[6:7], s[6:7], 12
	s_waitcnt vmcnt(4)
	v_lshl_add_u64 v[84:85], v[156:157], 0, s[6:7]
	global_load_dwordx4 v[96:99], v[84:85], off
	global_load_dwordx4 v[92:95], v[84:85], off offset:1024
	global_load_dwordx4 v[88:91], v[84:85], off offset:2048
	s_nop 0
	global_load_dwordx4 v[84:87], v[84:85], off offset:3072
	s_branch .Lidx_lddone0
.Lidx_dummy0:
	global_load_dword v173, v133, s[40:41]
	global_load_dword v173, v133, s[40:41]
	global_load_dword v173, v133, s[40:41]
	global_load_dword v173, v133, s[40:41]
.Lidx_lddone0:
.Lidx_entry0:
	s_cmp_gt_i32 s16, s13
	s_cbranch_scc1 .Lidx_exit_prev1
	s_waitcnt vmcnt(7)
	v_mfma_f32_32x32x16_bf16 v[20:35], v[44:47], v[80:83], 0
	s_waitcnt vmcnt(6)
	v_mfma_f32_32x32x16_bf16 v[20:35], v[48:51], v[76:79], v[20:35]
	s_waitcnt vmcnt(5)
	v_mfma_f32_32x32x16_bf16 v[20:35], v[52:55], v[72:75], v[20:35]
	s_waitcnt vmcnt(4)
	v_mfma_f32_32x32x16_bf16 v[20:35], v[56:59], v[68:71], v[20:35]
	s_cmp_lt_i32 s14, 0
	s_cbranch_scc1 .Lidx_nopost0
	v_max_i32_e32 v177, 0, v4
	v_max_i32_e32 v176, 0, v12
	v_max_i32_e32 v179, 0, v5
	v_pk_fma_f32 v[176:177], v[134:135], v[176:177], 0 op_sel_hi:[1,1,0]
	v_max_i32_e32 v178, 0, v13
	v_max_i32_e32 v181, 0, v6
	v_max_i32_e32 v180, 0, v14
	v_pk_fma_f32 v[176:177], v[36:37], v[178:179], v[176:177]
	v_lshl_or_b32 v188, s14, 5, v164
	v_pk_fma_f32 v[176:177], v[136:137], v[180:181], v[176:177]
	v_max_i32_e32 v179, 0, v7
	v_max_i32_e32 v178, 0, v15
	v_pk_fma_f32 v[176:177], v[38:39], v[178:179], v[176:177]
	v_max_i32_e32 v179, 0, v8
	v_max_i32_e32 v178, 0, v16
	v_pk_fma_f32 v[176:177], v[138:139], v[178:179], v[176:177]
	v_max_i32_e32 v179, 0, v9
	v_max_i32_e32 v178, 0, v17
	v_pk_fma_f32 v[176:177], v[40:41], v[178:179], v[176:177]
	v_max_i32_e32 v179, 0, v10
	v_max_i32_e32 v178, 0, v18
	v_pk_fma_f32 v[176:177], v[140:141], v[178:179], v[176:177]
	v_max_i32_e32 v179, 0, v11
	v_max_i32_e32 v178, 0, v19
	v_pk_fma_f32 v[176:177], v[42:43], v[178:179], v[176:177]
	s_nop 0
	v_and_b32_e32 v183, 0x7fffffff, v177
	v_and_b32_e32 v182, 0x7fffffff, v176
	v_xor_b32_e32 v185, -1, v177
	v_pk_add_f32 v[182:183], v[182:183], 0 neg_lo:[1,1] neg_hi:[1,1]
	v_cmp_gt_i32_e32 vcc, 0, v177
	v_xor_b32_e32 v184, -1, v176
	s_nop 0
	v_cndmask_b32_e32 v186, v183, v185, vcc
	v_cmp_gt_i32_e32 vcc, 0, v176
	s_nop 1
	v_cndmask_b32_e32 v187, v182, v184, vcc
	v_cmp_le_i32_e32 vcc, v188, v132
	s_nop 1
	v_cndmask_b32_e32 v187, 0, v187, vcc
	v_cmp_le_i32_e32 vcc, v188, v1
	v_lshl_add_u32 v189, s14, 7, v175
	s_nop 0
	v_cndmask_b32_e32 v186, 0, v186, vcc
	ds_write2st64_b32 v189, v186, v187 offset1:128
	v_lshrrev_b32_e32 v190, 20, v186
	v_cmp_eq_u32_e32 vcc, 0, v186
	v_lshrrev_b32_e32 v191, 17, v186
	v_and_b32_e32 v190, 0xffc, v190
	v_and_b32_e32 v191, 16, v191
	v_add_u32_e32 v190, v165, v190
	v_lshlrev_b32_e64 v191, v191, 1
	v_cndmask_b32_e32 v190, v190, v166, vcc
	v_cndmask_b32_e64 v191, v191, 0, vcc
	ds_add_u32 v190, v191
	v_lshrrev_b32_e32 v190, 20, v187
	v_cmp_eq_u32_e32 vcc, 0, v187
	v_lshrrev_b32_e32 v191, 17, v187
	v_and_b32_e32 v190, 0xffc, v190
	v_and_b32_e32 v191, 16, v191
	v_add3_u32 v190, v165, v190, s73
	v_lshlrev_b32_e64 v191, v191, 1
	v_cndmask_b32_e32 v190, v190, v166, vcc
	v_cndmask_b32_e64 v191, v191, 0, vcc
	ds_add_u32 v190, v191
	s_waitcnt lgkmcnt(3)
	s_branch .Lidx_join0

.Lidx_join0:
	v_readfirstlane_b32 s15, v171
	s_mov_b32 s14, s16
	s_mov_b32 s16, s15
	s_mov_b64 exec, 1
	ds_add_rtn_u32 v171, v172, v149
	s_mov_b64 exec, -1
	s_cmp_gt_i32 s16, s13
	s_cbranch_scc1 .Lidx_dummy1
	s_mov_b32 s6, s16
	s_ashr_i32 s7, s6, 31
	s_lshl_b64 s[6:7], s[6:7], 12
	s_waitcnt vmcnt(4)
	v_lshl_add_u64 v[68:69], v[156:157], 0, s[6:7]
	global_load_dwordx4 v[80:83], v[68:69], off
	global_load_dwordx4 v[76:79], v[68:69], off offset:1024
	global_load_dwordx4 v[72:75], v[68:69], off offset:2048
	s_nop 0
	global_load_dwordx4 v[68:71], v[68:69], off offset:3072
	s_branch .Lidx_lddone1

.Lidx_lddone1:
	s_cmp_gt_i32 s17, s13
	s_cbranch_scc1 .Lidx_exit_prev0
	s_waitcnt vmcnt(7)
	v_mfma_f32_32x32x16_bf16 v[4:19], v[44:47], v[96:99], 0
	s_waitcnt vmcnt(6)
	v_mfma_f32_32x32x16_bf16 v[4:19], v[48:51], v[92:95], v[4:19]
	s_waitcnt vmcnt(5)
	v_mfma_f32_32x32x16_bf16 v[4:19], v[52:55], v[88:91], v[4:19]
	s_waitcnt vmcnt(4)
	v_mfma_f32_32x32x16_bf16 v[4:19], v[56:59], v[84:87], v[4:19]
	v_max_i32_e32 v177, 0, v20
	v_max_i32_e32 v176, 0, v28
	v_max_i32_e32 v179, 0, v21
	v_pk_fma_f32 v[176:177], v[134:135], v[176:177], 0 op_sel_hi:[1,1,0]
	v_max_i32_e32 v178, 0, v29
	v_max_i32_e32 v181, 0, v22
	v_max_i32_e32 v180, 0, v30
	v_pk_fma_f32 v[176:177], v[36:37], v[178:179], v[176:177]
	v_lshl_or_b32 v188, s14, 5, v164
	v_pk_fma_f32 v[176:177], v[136:137], v[180:181], v[176:177]
	v_max_i32_e32 v179, 0, v23
	v_max_i32_e32 v178, 0, v31
	v_pk_fma_f32 v[176:177], v[38:39], v[178:179], v[176:177]
	v_max_i32_e32 v179, 0, v24
	v_max_i32_e32 v178, 0, v32
	v_pk_fma_f32 v[176:177], v[138:139], v[178:179], v[176:177]
	v_max_i32_e32 v179, 0, v25
	v_max_i32_e32 v178, 0, v33
	v_pk_fma_f32 v[176:177], v[40:41], v[178:179], v[176:177]
	v_max_i32_e32 v179, 0, v26
	v_max_i32_e32 v178, 0, v34
	v_pk_fma_f32 v[176:177], v[140:141], v[178:179], v[176:177]
	v_max_i32_e32 v179, 0, v27
	v_max_i32_e32 v178, 0, v35
	v_pk_fma_f32 v[176:177], v[42:43], v[178:179], v[176:177]
	s_nop 0
	v_and_b32_e32 v183, 0x7fffffff, v177
	v_and_b32_e32 v182, 0x7fffffff, v176
	v_xor_b32_e32 v185, -1, v177
	v_pk_add_f32 v[182:183], v[182:183], 0 neg_lo:[1,1] neg_hi:[1,1]
	v_cmp_gt_i32_e32 vcc, 0, v177
	v_xor_b32_e32 v184, -1, v176
	s_nop 0
	v_cndmask_b32_e32 v186, v183, v185, vcc
	v_cmp_gt_i32_e32 vcc, 0, v176
	s_nop 1
	v_cndmask_b32_e32 v187, v182, v184, vcc
	v_cmp_le_i32_e32 vcc, v188, v132
	s_nop 1
	v_cndmask_b32_e32 v187, 0, v187, vcc
	v_cmp_le_i32_e32 vcc, v188, v1
	v_lshl_add_u32 v189, s14, 7, v175
	s_nop 0
	v_cndmask_b32_e32 v186, 0, v186, vcc
	ds_write2st64_b32 v189, v186, v187 offset1:128
	v_lshrrev_b32_e32 v190, 20, v186
	v_cmp_eq_u32_e32 vcc, 0, v186
	v_lshrrev_b32_e32 v191, 17, v186
	v_and_b32_e32 v190, 0xffc, v190
	v_and_b32_e32 v191, 16, v191
	v_add_u32_e32 v190, v165, v190
	v_lshlrev_b32_e64 v191, v191, 1
	v_cndmask_b32_e32 v190, v190, v166, vcc
	v_cndmask_b32_e64 v191, v191, 0, vcc
	ds_add_u32 v190, v191
	v_lshrrev_b32_e32 v190, 20, v187
	v_cmp_eq_u32_e32 vcc, 0, v187
	v_lshrrev_b32_e32 v191, 17, v187
	v_and_b32_e32 v190, 0xffc, v190
	v_and_b32_e32 v191, 16, v191
	v_add3_u32 v190, v165, v190, s73
	v_lshlrev_b32_e64 v191, v191, 1
	v_cndmask_b32_e32 v190, v190, v166, vcc
	v_cndmask_b32_e64 v191, v191, 0, vcc
	ds_add_u32 v190, v191
	s_waitcnt lgkmcnt(3)
	v_readfirstlane_b32 s15, v171
	s_add_i32 s10, s10, 1
	s_cmpk_lt_i32 s10, 0x400
	s_cbranch_scc1 .Lidx_loop
	s_branch .Lidx_done

.LBB0_729:
	s_ashr_i32 s90, s60, 7
	s_lshl_b32 s6, s90, 5
	s_add_i32 s61, s6, 0
	s_add_i32 s91, s61, 0x25800
	v_mov_b32_e32 v1, s91
	s_waitcnt lgkmcnt(0)
	s_barrier
	ds_read_b32 v8, v1
	s_lshl_b32 s57, s13, 3
	s_add_i32 s57, s57, 8
	v_and_or_b32 v3, s60, 64, v145
	s_lshl_b32 s89, s90, 15
	v_cmp_gt_i32_e64 s[12:13], s57, v3
	v_mov_b32_e32 v4, 0
	s_waitcnt lgkmcnt(0)
	v_lshlrev_b32_e32 v176, 21, v8
	v_or_b32_e32 v177, 0x1fffff, v176
	v_mov_b32_e32 v178, 0
	v_mov_b32_e32 v179, 0
	v_mov_b32_e32 v180, 0
	v_mov_b32_e32 v181, 0
	v_mov_b32_e32 v182, 0
	v_mov_b32_e32 v183, 0
	s_and_saveexec_b64 s[6:7], s[12:13]
	s_cbranch_execz .LBB0_733
	s_lshl_b32 s10, s60, 4
	s_and_b32 s10, s10, 0x400
	s_add_i32 s10, s89, s10
	s_add_i32 s10, s10, 0
	v_lshl_add_u32 v1, v145, 4, s10
	s_mov_b64 s[10:11], 0
	v_mov_b32_e32 v5, v3
	s_mov_b32 s33, 0
.Lcls_p1:
	ds_read_b128 v[10:13], v1
	v_add_u32_e32 v5, 0x80, v5
	v_cmp_le_i32_e32 vcc, s57, v5
	s_or_b64 s[10:11], vcc, s[10:11]
	v_add_u32_e32 v1, 0x800, v1
	s_waitcnt lgkmcnt(0)
	v_cmp_ge_u32_e64 s[16:17], v10, v176
	v_cmp_ge_u32_e64 s[18:19], v11, v176
	v_cmp_ge_u32_e64 s[22:23], v12, v176
	v_cmp_ge_u32_e64 s[24:25], v13, v176
	v_cndmask_b32_e64 v184, 0, 1, s[16:17]
	v_cndmask_b32_e64 v185, 0, 2, s[18:19]
	v_cndmask_b32_e64 v186, 0, 4, s[22:23]
	v_cndmask_b32_e64 v187, 0, 8, s[24:25]
	v_cmp_gt_u32_e64 s[16:17], v10, v177
	v_cmp_gt_u32_e64 s[18:19], v11, v177
	v_cmp_gt_u32_e64 s[22:23], v12, v177
	v_cmp_gt_u32_e64 s[24:25], v13, v177
	v_or3_b32 v188, v184, v185, v186
	v_or_b32_e32 v188, v188, v187
	v_cndmask_b32_e64 v184, 0, 1, s[16:17]
	v_cndmask_b32_e64 v185, 0, 2, s[18:19]
	v_cndmask_b32_e64 v186, 0, 4, s[22:23]
	v_cndmask_b32_e64 v187, 0, 8, s[24:25]
	v_bcnt_u32_b32 v182, v188, v182
	v_or3_b32 v189, v184, v185, v186
	v_or_b32_e32 v189, v189, v187
	s_cmp_lt_u32 s33, 32
	v_bcnt_u32_b32 v183, v189, v183
	s_cbranch_scc0 .Lcls_p1_hi
	v_lshl_or_b32 v178, v188, s33, v178
	v_lshl_or_b32 v180, v189, s33, v180
	s_branch .Lcls_p1_join
.Lcls_p1_hi:
	s_sub_u32 s58, s33, 32
	v_lshl_or_b32 v179, v188, s58, v179
	v_lshl_or_b32 v181, v189, s58, v181
.Lcls_p1_join:
	s_add_u32 s33, s33, 4
	s_andn2_b64 exec, exec, s[10:11]
	s_cbranch_execnz .Lcls_p1
	s_or_b64 exec, exec, s[10:11]
	v_sub_u32_e32 v184, v182, v183
	v_lshl_or_b32 v4, v184, 16, v183

.LBB0_743:
	s_or_b64 exec, exec, s[16:17]
	v_lshlrev_b32_e32 v11, 2, v1
	s_waitcnt lgkmcnt(0)
	ds_bpermute_b32 v7, v11, v9
	ds_bpermute_b32 v6, v11, v6
	s_and_saveexec_b64 s[16:17], s[12:13]
	s_cbranch_execz .LBB0_778
	s_lshl_b32 s18, s60, 4
	s_and_b32 s18, s18, 0x400
	s_lshl_b32 s92, s90, 9
	s_add_i32 s18, s89, s18
	v_sub_u32_e32 v4, v5, v4
	s_add_i32 s93, s92, 0
	s_add_i32 s18, s18, 0
	s_waitcnt lgkmcnt(0)
	v_add_u32_sdwa v9, v6, v4 dst_sel:DWORD dst_unused:UNUSED_PAD src0_sel:DWORD src1_sel:WORD_1
	v_add_u32_e32 v11, v7, v4
	s_add_i32 s93, s93, 0x24000
	v_mov_b32_e32 v199, 0x1000
	v_lshlrev_b32_e32 v190, 2, v3
	v_xor_b32_e32 v178, v178, v180
	v_xor_b32_e32 v179, v179, v181
.Lcls_A_lo:
	v_cmp_ne_u32_e32 vcc, 0, v180
	s_cbranch_vccz .Lcls_A_lo_done
	s_and_saveexec_b64 s[18:19], vcc
	v_ffbl_b32_e32 v191, v180
	v_add_u32_e32 v193, -1, v180
	v_and_b32_e32 v180, v180, v193
	v_and_b32_e32 v193, 60, v191
	v_lshl_add_u32 v192, v193, 7, v190
	v_and_b32_e32 v193, 3, v191
	v_add_u32_e32 v192, v192, v193
	v_and_b32_e32 v193, 0xff, v11
	v_lshl_add_u32 v193, v193, 1, s93
	v_add_u32_e32 v11, 1, v11
	ds_write_b16 v193, v192
	s_mov_b64 exec, s[18:19]
	s_branch .Lcls_A_lo
.Lcls_A_lo_done:
.Lcls_A_hi:
	v_cmp_ne_u32_e32 vcc, 0, v181
	s_cbranch_vccz .Lcls_A_hi_done
	s_and_saveexec_b64 s[18:19], vcc
	v_ffbl_b32_e32 v191, v181
	v_add_u32_e32 v193, -1, v181
	v_and_b32_e32 v181, v181, v193
	v_and_b32_e32 v193, 60, v191
	v_lshl_add_u32 v192, v193, 7, v190
	v_and_b32_e32 v193, 3, v191
	v_add3_u32 v192, v192, v193, v199
	v_and_b32_e32 v193, 0xff, v11
	v_lshl_add_u32 v193, v193, 1, s93
	v_add_u32_e32 v11, 1, v11
	ds_write_b16 v193, v192
	s_mov_b64 exec, s[18:19]
	s_branch .Lcls_A_hi
.Lcls_A_hi_done:
.Lcls_C_lo:
	v_cmp_ne_u32_e32 vcc, 0, v178
	s_cbranch_vccz .Lcls_C_lo_done
	s_and_saveexec_b64 s[18:19], vcc
	v_ffbl_b32_e32 v191, v178
	v_add_u32_e32 v193, -1, v178
	v_and_b32_e32 v178, v178, v193
	v_and_b32_e32 v193, 60, v191
	v_lshl_add_u32 v192, v193, 7, v190
	v_and_b32_e32 v193, 3, v191
	v_add_u32_e32 v192, v192, v193
	v_lshl_add_u32 v195, v192, 2, s89
	ds_read_b32 v194, v195
	v_cmp_gt_u32_e32 vcc, s69, v9
	v_or_b32_e32 v196, s92, v9
	v_lshl_add_u32 v197, v196, 2, s68
	v_lshl_add_u32 v198, v196, 1, s68
	v_add_u32_e32 v9, 1, v9
	s_and_b64 exec, exec, vcc
	s_waitcnt lgkmcnt(0)
	ds_write_b32 v197, v194
	ds_write_b16 v198, v192 offset:8192
	s_mov_b64 exec, s[18:19]
	s_branch .Lcls_C_lo
.Lcls_C_lo_done:
.Lcls_C_hi:
	v_cmp_ne_u32_e32 vcc, 0, v179
	s_cbranch_vccz .Lcls_C_hi_done
	s_and_saveexec_b64 s[18:19], vcc
	v_ffbl_b32_e32 v191, v179
	v_add_u32_e32 v193, -1, v179
	v_and_b32_e32 v179, v179, v193
	v_and_b32_e32 v193, 60, v191
	v_lshl_add_u32 v192, v193, 7, v190
	v_and_b32_e32 v193, 3, v191
	v_add3_u32 v192, v192, v193, v199
	v_lshl_add_u32 v195, v192, 2, s89
	ds_read_b32 v194, v195
	v_cmp_gt_u32_e32 vcc, s69, v9
	v_or_b32_e32 v196, s92, v9
	v_lshl_add_u32 v197, v196, 2, s68
	v_lshl_add_u32 v198, v196, 1, s68
	v_add_u32_e32 v9, 1, v9
	s_and_b64 exec, exec, vcc
	s_waitcnt lgkmcnt(0)
	ds_write_b32 v197, v194
	ds_write_b16 v198, v192 offset:8192
	s_mov_b64 exec, s[18:19]
	s_branch .Lcls_C_hi
.Lcls_C_hi_done:
.LBB0_778:
	s_or_b64 exec, exec, s[16:17]
	v_mov_b32_e32 v4, s75
	s_waitcnt lgkmcnt(0)
	s_barrier
	ds_read_b32 v4, v4
	s_waitcnt lgkmcnt(0)
	v_cmp_gt_u32_e32 vcc, s82, v4
	v_cmp_lt_u32_e64 s[18:19], s69, v4
	s_cbranch_vccz .LBB0_782
	v_mov_b32_e32 v4, s83
	ds_read_b32 v4, v4
	s_waitcnt lgkmcnt(0)
	v_cmp_gt_u32_e32 vcc, s82, v4
	v_cmp_lt_u32_e64 s[18:19], s69, v4
	s_cbranch_vccz .LBB0_782
	v_mov_b32_e32 v4, s84
	ds_read_b32 v4, v4
	s_waitcnt lgkmcnt(0)
	v_cmp_gt_u32_e32 vcc, s82, v4
	v_cmp_lt_u32_e64 s[18:19], s69, v4
	s_cbranch_vccz .LBB0_782
	v_mov_b32_e32 v4, s85
	ds_read_b32 v4, v4
	s_mov_b64 s[16:17], -1
	s_waitcnt lgkmcnt(0)
	v_cmp_lt_u32_e64 s[18:19], s69, v4
	s_and_b64 vcc, exec, s[18:19]
	s_cbranch_vccnz .LBB0_783
	s_branch .LBB0_875

.LBB0_975:
	s_or_b64 exec, exec, s[4:5]
	v_mov_b32_e32 v15, v202
	s_add_u32 s62, s28, 0x14000000
	s_waitcnt lgkmcnt(0)
	s_barrier
	s_nop 0
	s_nop 0
	s_nop 0
	s_nop 0
	s_nop 0
	s_nop 0
	s_nop 0
	s_nop 0
	s_nop 0
	s_nop 0
	s_nop 0
	s_nop 0
	s_nop 0
	s_nop 0
	s_nop 0
	s_nop 0
	s_nop 0
	s_nop 0
	s_nop 0
	s_nop 0
	s_nop 0
	s_nop 0
	s_nop 0
	s_nop 0
	s_nop 0
	s_nop 0
	s_nop 0
	s_nop 0
	s_nop 0
	s_nop 0
	s_nop 0
	s_nop 0
	s_nop 0
	s_nop 0
	s_nop 0
	s_nop 0
	s_nop 0
	s_nop 0
	s_nop 0
	s_nop 0
	s_nop 0
	s_nop 0
	s_nop 0
	s_nop 0
	s_nop 0
	s_nop 0
	s_nop 0
	s_nop 0
	s_nop 0
	s_nop 0
	s_nop 0
	s_nop 0
	s_nop 0
	s_nop 0
	s_nop 0
	s_nop 0
	s_nop 0
	s_nop 0
	s_nop 0
	s_addc_u32 s63, s29, 0
	v_readfirstlane_b32 s4, v15
	s_ashr_i32 s4, s4, 6
	s_and_b64 s[6:7], s[46:47], exec
	s_cselect_b32 s5, 8, 1
	v_cvt_f32_ubyte0_e32 v1, s5
	v_rcp_iflag_f32_e32 v1, v1
	s_add_i32 s8, s5, -1
	s_and_b64 s[6:7], s[46:47], exec
	s_cselect_b32 s24, 3, 0
	v_mul_f32_e32 v1, 0x4f7ffffe, v1
	v_cvt_u32_f32_e32 v1, v1
	s_sub_i32 s9, 0, s5
	s_abs_i32 s7, s30
	s_lshr_b32 s6, s2, s24
	v_readfirstlane_b32 s10, v1
	s_mul_i32 s9, s9, s10
	s_mul_hi_u32 s9, s10, s9
	s_add_i32 s10, s10, s9
	s_mul_hi_u32 s9, s7, s10
	s_mul_i32 s10, s9, s5
	s_sub_i32 s7, s7, s10
	s_lshl_b32 s6, s6, 3
	s_ashr_i32 s68, s30, 31
	s_add_i32 s10, s9, 1
	s_sub_i32 s11, s7, s5
	s_cmp_ge_u32 s7, s5
	s_cselect_b32 s9, s10, s9
	s_cselect_b32 s7, s11, s7
	s_add_i32 s10, s9, 1
	s_cmp_ge_u32 s7, s5
	s_cselect_b32 s7, s10, s9
	s_xor_b32 s7, s7, s68
	s_sub_i32 s7, s7, s68
	s_lshl_b32 s25, s7, 3
	s_abs_i32 s7, s25
	v_cvt_f32_u32_e32 v1, s7
	s_add_i32 s40, s4, s6
	s_sub_i32 s6, s25, s40
	s_and_b32 s41, s8, s2
	v_rcp_iflag_f32_e32 v1, v1
	s_add_i32 s8, s6, 0x1fff
	s_sub_i32 s6, 0xffffe001, s6
	s_xor_b32 s9, s8, s25
	v_mul_f32_e32 v1, 0x4f7ffffe, v1
	v_cvt_u32_f32_e32 v1, v1
	s_max_i32 s6, s8, s6
	s_sub_i32 s8, 0, s7
	s_ashr_i32 s9, s9, 31
	v_readfirstlane_b32 s10, v1
	s_mul_i32 s8, s8, s10
	s_mul_hi_u32 s8, s10, s8
	s_add_i32 s10, s10, s8
	s_mul_hi_u32 s8, s6, s10
	s_mul_i32 s10, s8, s7
	s_sub_i32 s6, s6, s10
	s_add_i32 s10, s8, 1
	s_sub_i32 s11, s6, s7
	s_cmp_ge_u32 s6, s7
	s_cselect_b32 s8, s10, s8
	s_cselect_b32 s6, s11, s6
	s_add_i32 s10, s8, 1
	s_cmp_ge_u32 s6, s7
	s_cselect_b32 s6, s10, s8
	s_sub_i32 s5, s5, s41
	s_xor_b32 s6, s6, s9
	s_add_i32 s5, s5, 15
	s_sub_i32 s42, s6, s9
	s_lshr_b32 s5, s5, s24
	s_mul_i32 s43, s42, s5
	s_cmp_lt_i32 s43, 1
	s_mov_b32 s9, 0
	s_cbranch_scc1 .LBB0_980
	s_lshl_b32 s5, s4, 14
	s_lshl_b32 s4, s4, 10
	s_add_i32 s47, s4, 0
	s_lshr_b32 s8, s41, 2
	s_add_i32 s46, s5, 0
	s_add_i32 s47, s47, 0x20000
	s_and_b32 s10, s41, 3
	s_lshl_b64 s[4:5], s[8:9], 13
	s_ashr_i32 s6, s40, 31
	s_add_u32 s4, s4, s40
	s_addc_u32 s5, s5, s6
	s_lshl_b64 s[6:7], s[4:5], 9
	v_and_b32_e32 v14, 63, v15
	s_add_u32 s6, s44, s6
	s_addc_u32 s7, s45, s7
	v_lshlrev_b32_e32 v42, 3, v14
	global_load_dwordx2 v[2:3], v42, s[6:7]
	v_and_b32_e32 v17, 15, v15
	v_bfe_u32 v4, v15, 4, 2
	v_bfe_u32 v6, v15, 2, 2
	v_and_b32_e32 v1, 7, v15
	v_lshlrev_b32_e32 v34, 3, v15
	v_mov_b32_e32 v7, 0x1000
	v_lshrrev_b32_e32 v9, 3, v15
	v_or_b32_e32 v12, 16, v17
	v_lshl_or_b32 v6, v4, 2, v6
	v_bfe_u32 v5, v15, 3, 1
	v_and_b32_e32 v10, 1, v15
	v_bitop3_b32 v13, v4, v1, 4 bitop3:0x36
	v_bitop3_b32 v16, v4, v15, 7 bitop3:0x78
	v_and_or_b32 v7, v34, 24, v7
	v_xor_b32_e32 v9, v9, v15
	v_mul_u32_u24_e32 v21, 0x40004, v14
	v_lshrrev_b32_e32 v22, 3, v12
	v_lshlrev_b32_e32 v24, 4, v6
	v_lshlrev_b32_e32 v6, 7, v6
	s_cmpk_gt_i32 s40, 0xff
	s_movk_i32 s6, 0x60
	v_lshlrev_b32_e32 v12, 7, v12
	v_xor_b32_e32 v23, v13, v5
	v_xor_b32_e32 v5, v16, v5
	v_and_or_b32 v9, v9, 6, v10
	v_or_b32_e32 v60, 0x10000, v21
	v_or_b32_e32 v61, 0x30002, v21
	v_xor_b32_e32 v10, v13, v22
	v_xor_b32_e32 v13, v16, v22
	v_or_b32_e32 v16, 0x800, v6
	v_or_b32_e32 v6, v6, v7
	s_cselect_b64 vcc, -1, 0
	v_lshlrev_b32_e32 v11, 6, v15
	s_waitcnt vmcnt(2)
	v_lshlrev_b32_e32 v52, 4, v9
	v_add_u32_e32 v9, s47, v42
	v_lshl_or_b32 v37, v10, 4, v12
	v_bitop3_b32 v10, v24, v16, s6 bitop3:0xce
	v_bitop3_b32 v39, v24, v6, s6 bitop3:0xce
	s_mul_hi_u32 s6, s4, 0x1200
	s_mulk_i32 s5, 0x1200
	s_mulk_i32 s4, 0x1200
	s_add_i32 s6, s6, s5
	v_mov_b32_e32 v43, 0
	s_add_u32 s4, s38, s4
	v_mov_b32_e32 v8, 0x60
	v_lshlrev_b32_e32 v19, 7, v17
	s_addc_u32 s5, s39, s6
	v_lshl_or_b32 v35, v23, 4, v19
	v_lshl_or_b32 v36, v5, 4, v19
	v_and_b32_e32 v5, 0x60, v24
	v_bitop3_b32 v19, v24, 64, v8 bitop3:0x6c
	v_bitop3_b32 v8, v24, 32, v8 bitop3:0x6c
	v_bfe_u32 v18, v15, 3, 3
	v_lshl_or_b32 v38, v13, 4, v12
	v_or_b32_e32 v12, v19, v16
	v_or_b32_e32 v13, v8, v16
	v_or_b32_e32 v41, v8, v6
	v_or_b32_e32 v8, v5, v16
	s_waitcnt vmcnt(1)
	v_or_b32_e32 v56, v6, v5
	v_lshlrev_b32_e32 v16, 3, v4
	v_and_b32_e32 v4, 48, v15
	v_mov_b32_e32 v5, v43
	v_lshlrev_b32_e32 v63, 6, v18
	v_bitop3_b32 v20, v18, v15, 7 bitop3:0x78
	v_or_b32_e32 v40, v19, v6
	v_add_u32_e32 v57, v10, v7
	v_add_u32_e32 v58, v12, v7
	v_add_u32_e32 v59, v13, v7
	v_add_u32_e32 v90, v8, v7
	v_add_u32_e32 v18, s47, v63
	v_mov_b32_e32 v19, v43
	v_lshlrev_b32_e32 v44, 4, v20
	v_mov_b32_e32 v45, v43
	s_mov_b32 m0, s46
	v_mov_b32_e32 v53, v43
	v_mov_b32_e32 v64, 9
	v_xor_b32_e32 v50, 16, v44
	v_mov_b32_e32 v51, v43
	v_xor_b32_e32 v48, 32, v44
	s_waitcnt vmcnt(0)
	v_cndmask_b32_e32 v2, v60, v2, vcc
	v_cndmask_b32_e32 v3, v61, v3, vcc
	ds_write_b64 v9, v[2:3]
	v_and_b32_e32 v2, 0xc0, v11
	v_lshlrev_b32_e32 v62, 1, v2
	v_lshl_or_b32 v2, s10, 9, v62
	v_mov_b32_e32 v3, v43
	v_lshl_add_u64 v[2:3], s[4:5], 0, v[2:3]
	s_lshl_b64 s[4:5], s[8:9], 22
	s_add_u32 s6, s80, s4
	v_lshl_add_u64 v[2:3], v[2:3], 0, v[4:5]
	s_addc_u32 s7, s81, s5
	global_load_dwordx4 v[10:13], v[2:3], off
	global_load_dwordx4 v[6:9], v[2:3], off offset:64
	s_waitcnt lgkmcnt(0)
	s_add_u32 s4, s37, s4
	ds_read_b128 v[30:33], v18
	ds_read_b128 v[22:25], v18 offset:16
	ds_read_b128 v[2:5], v18 offset:32
	ds_read_b128 v[26:29], v18 offset:48
	s_addc_u32 s5, s79, s5
	s_lshl_b32 s8, s10, 7
	s_add_u32 s4, s4, s8
	s_addc_u32 s5, s5, 0
	s_waitcnt lgkmcnt(3)
	v_lshlrev_b32_e32 v18, 9, v30
	s_add_u32 s6, s6, s8
	v_and_b32_e32 v18, 0x1fffe00, v18
	s_addc_u32 s7, s7, 0
	v_lshl_add_u64 v[20:21], s[4:5], 0, v[18:19]
	s_add_i32 s48, s46, 0x1000
	v_lshl_add_u64 v[20:21], v[20:21], 0, v[44:45]
	v_lshl_add_u64 v[18:19], s[6:7], 0, v[18:19]
	global_load_lds_dwordx4 v[20:21], off
	v_lshl_add_u64 v[18:19], v[18:19], 0, v[52:53]
	s_mov_b32 m0, s48
	s_add_i32 s49, s46, 0x400
	global_load_lds_dwordx4 v[18:19], off
	v_lshlrev_b32_sdwa v18, v64, v30 dst_sel:DWORD dst_unused:UNUSED_PAD src0_sel:DWORD src1_sel:WORD_1
	v_mov_b32_e32 v19, v43
	v_lshl_add_u64 v[20:21], s[4:5], 0, v[18:19]
	v_lshl_add_u64 v[20:21], v[20:21], 0, v[50:51]
	s_mov_b32 m0, s49
	v_lshl_add_u64 v[18:19], s[6:7], 0, v[18:19]
	s_add_i32 s50, s46, 0x1400
	global_load_lds_dwordx4 v[20:21], off
	v_lshl_add_u64 v[18:19], v[18:19], 0, v[52:53]
	s_mov_b32 m0, s50
	v_mov_b32_e32 v49, v43
	global_load_lds_dwordx4 v[18:19], off
	v_lshlrev_b32_e32 v18, 9, v31
	v_and_b32_e32 v18, 0x1fffe00, v18
	v_mov_b32_e32 v19, v43
	v_lshl_add_u64 v[20:21], s[4:5], 0, v[18:19]
	s_add_i32 s51, s46, 0x800
	v_lshl_add_u64 v[20:21], v[20:21], 0, v[48:49]
	s_mov_b32 m0, s51
	v_lshl_add_u64 v[18:19], s[6:7], 0, v[18:19]
	s_add_i32 s52, s46, 0x1800
	global_load_lds_dwordx4 v[20:21], off
	v_lshl_add_u64 v[18:19], v[18:19], 0, v[52:53]
	s_mov_b32 m0, s52
	v_xor_b32_e32 v46, 48, v44
	global_load_lds_dwordx4 v[18:19], off
	v_lshlrev_b32_sdwa v18, v64, v31 dst_sel:DWORD dst_unused:UNUSED_PAD src0_sel:DWORD src1_sel:WORD_1
	v_mov_b32_e32 v19, v43
	v_lshl_add_u64 v[20:21], s[4:5], 0, v[18:19]
	v_mov_b32_e32 v47, v43
	s_add_i32 s53, s46, 0xc00
	v_lshl_add_u64 v[20:21], v[20:21], 0, v[46:47]
	s_mov_b32 m0, s53
	v_lshl_add_u64 v[18:19], s[6:7], 0, v[18:19]
	s_add_i32 s54, s46, 0x1c00
	global_load_lds_dwordx4 v[20:21], off
	v_lshl_add_u64 v[18:19], v[18:19], 0, v[52:53]
	s_mov_b32 m0, s54
	v_cmp_gt_u32_e64 s[4:5], 4, v17
	global_load_lds_dwordx4 v[18:19], off
	v_and_b32_e32 v17, 0x80, v34
	v_bfe_u32 v15, v15, 5, 1
	v_or_b32_e32 v19, 32, v17
	v_or_b32_e32 v20, 64, v17
	v_or_b32_e32 v21, 0x60, v17
	v_or_b32_e32 v30, 6, v15
	v_or_b32_e32 v82, v17, v30
	v_or_b32_e32 v84, v19, v30
	v_or_b32_e32 v86, v20, v30
	v_or_b32_e32 v88, v21, v30
	v_or_b32_e32 v30, 10, v15
	v_or_b32_e32 v18, 2, v15
	v_or_b32_e32 v98, v17, v30
	v_or_b32_e32 v100, v19, v30
	v_or_b32_e32 v102, v20, v30
	v_or_b32_e32 v104, v21, v30
	v_or_b32_e32 v30, 14, v15
	v_or_b32_e32 v66, v17, v18
	v_or_b32_e32 v68, v19, v18
	v_or_b32_e32 v70, v20, v18
	v_or_b32_e32 v72, v21, v18
	v_or_b32_e32 v18, 4, v15
	v_or_b32_e32 v106, v17, v30
	v_or_b32_e32 v108, v19, v30
	v_or_b32_e32 v110, v20, v30
	v_or_b32_e32 v112, v21, v30
	v_or_b32_e32 v30, 18, v15
	v_or_b32_e32 v81, v17, v18
	v_or_b32_e32 v83, v19, v18
	v_or_b32_e32 v85, v20, v18
	v_or_b32_e32 v87, v21, v18
	v_or_b32_e32 v18, 8, v15
	v_or_b32_e32 v114, v17, v30
	v_or_b32_e32 v116, v19, v30
	v_or_b32_e32 v118, v20, v30
	v_or_b32_e32 v120, v21, v30
	v_or_b32_e32 v30, 22, v15
	v_lshl_add_u64 v[54:55], s[44:45], 0, v[42:43]
	v_or_b32_e32 v97, v17, v18
	v_or_b32_e32 v99, v19, v18
	v_or_b32_e32 v101, v20, v18
	v_or_b32_e32 v103, v21, v18
	v_or_b32_e32 v18, 12, v15
	v_or_b32_e32 v122, v17, v30
	v_or_b32_e32 v124, v19, v30
	v_or_b32_e32 v126, v20, v30
	v_or_b32_e32 v128, v21, v30
	v_or_b32_e32 v30, 26, v15
	s_abs_i32 s45, s42
	v_or_b32_e32 v105, v17, v18
	v_or_b32_e32 v107, v19, v18
	v_or_b32_e32 v109, v20, v18
	v_or_b32_e32 v111, v21, v18
	v_or_b32_e32 v18, 16, v15
	v_or_b32_e32 v130, v17, v30
	v_or_b32_e32 v132, v19, v30
	v_or_b32_e32 v134, v20, v30
	v_or_b32_e32 v136, v21, v30
	v_cvt_f32_u32_e32 v30, s45
	v_or_b32_e32 v113, v17, v18
	v_or_b32_e32 v115, v19, v18
	v_or_b32_e32 v117, v20, v18
	v_or_b32_e32 v119, v21, v18
	v_or_b32_e32 v18, 20, v15
	v_or_b32_e32 v121, v17, v18
	v_or_b32_e32 v123, v19, v18
	v_or_b32_e32 v125, v20, v18
	v_or_b32_e32 v127, v21, v18
	v_or_b32_e32 v18, 24, v15
	v_or_b32_e32 v65, v17, v15
	v_or_b32_e32 v67, v19, v15
	v_or_b32_e32 v69, v20, v15
	v_or_b32_e32 v71, v21, v15
	v_or_b32_e32 v129, v17, v18
	v_or_b32_e32 v131, v19, v18
	v_or_b32_e32 v133, v20, v18
	v_or_b32_e32 v135, v21, v18
	v_or_b32_e32 v18, 28, v15
	v_or_b32_e32 v15, 30, v15
	v_or_b32_e32 v137, v17, v18
	v_or_b32_e32 v138, v17, v15
	v_rcp_iflag_f32_e32 v17, v30
	s_sub_i32 s8, 0, s45
	s_add_i32 s44, s46, 0x2000
	v_lshlrev_b32_e32 v1, 2, v14
	v_mul_f32_e32 v17, 0x4f7ffffe, v17
	v_cvt_u32_f32_e32 v17, v17
	s_waitcnt vmcnt(0)
	v_cndmask_b32_e64 v9, 0, v9, s[4:5]
	v_cndmask_b32_e64 v8, 0, v8, s[4:5]
	v_cndmask_b32_e64 v7, 0, v7, s[4:5]
	v_readfirstlane_b32 s10, v17
	s_mul_i32 s8, s8, s10
	s_mul_hi_u32 s8, s10, s8
	v_cndmask_b32_e64 v6, 0, v6, s[4:5]
	v_cndmask_b32_e64 v13, 0, v13, s[4:5]
	v_cndmask_b32_e64 v12, 0, v12, s[4:5]
	v_cndmask_b32_e64 v11, 0, v11, s[4:5]
	v_cndmask_b32_e64 v10, 0, v10, s[4:5]
	v_cmp_gt_u32_e64 s[6:7], 16, v14
	v_add_u32_e32 v73, s46, v56
	v_add_u32_e32 v74, s46, v90
	v_add_u32_e32 v75, s46, v41
	v_add_u32_e32 v76, s46, v59
	v_add_u32_e32 v77, s46, v40
	v_add_u32_e32 v78, s46, v58
	v_add_u32_e32 v79, s46, v39
	v_add_u32_e32 v80, s46, v57
	v_add_u32_e32 v89, s44, v56
	v_add_u32_e32 v90, s44, v90
	v_add_u32_e32 v91, s44, v41
	v_add_u32_e32 v92, s44, v59
	v_add_u32_e32 v93, s44, v40
	v_add_u32_e32 v94, s44, v58
	v_add_u32_e32 v95, s44, v39
	v_add_u32_e32 v96, s44, v57
	v_or_b32_e32 v139, v19, v18
	v_or_b32_e32 v140, v19, v15
	v_or_b32_e32 v141, v20, v18
	v_or_b32_e32 v142, v20, v15
	v_or_b32_e32 v143, v21, v18
	v_or_b32_e32 v144, v21, v15
	s_ashr_i32 s55, s42, 31
	s_add_i32 s56, s10, s8
	s_sub_i32 s57, 0, s42
	v_lshlrev_b32_e32 v56, 1, v16
	s_add_i32 s58, s46, 0x3000
	s_add_i32 s59, s46, 0x2400
	s_add_i32 s60, s46, 0x3400
	s_add_i32 s61, s46, 0x2800
	s_add_i32 s64, s46, 0x3800
	s_add_i32 s65, s46, 0x2c00
	s_add_i32 s66, s46, 0x3c00
	v_add_u32_e32 v145, s46, v36
	v_add_u32_e32 v149, s46, v35
	v_add_u32_e32 v151, s46, v38
	v_add_u32_e32 v153, s46, v37
	v_lshlrev_b32_e32 v58, 1, v14
	s_movk_i32 s67, 0x7fff
	s_mov_b32 s69, 0
	s_mov_b32 s70, 0
	s_branch .LBB0_978
